# v36 + rwkv_post r*k row-dot groups: loads and address arithmetic of groups 2-4 issued with group 1 (dependency-slice hoist into spare registers): one load round trip per row half instead of four
# speedup vs baseline: 1.0060x; 1.0060x over previous
; #define LAS __attribute__((address_space(3)))
; DI f32x4 mma16(bf16x8 a, bf16x8 b, f32x4 c) { return __builtin_amdgcn_mfma_f32_16x16x32_bf16(a, b, c, 0, 0, 0); }
; DI void rwkv_post_item(KA a, const int l, LAS unsigned char* lds, const int tile) {
;     ...
;     const int hd = w >> 1, th = w & 1;
;     f32x4 accg[4][2];
; #pragma unroll
;     for (int ct = 0; ct < 4; ++ct) { accg[ct][0] = ZERO4; accg[ct][1] = ZERO4; }
;     const bf16* g2T = (const bf16*)(ws + WS_SMALL + l * SMALL_STRIDE + SM_G2T);
; #pragma unroll
;     for (int ks = 0; ks < 5; ++ks) {
;         bf16x8 af[2];
; #pragma unroll
;         for (int rt = 0; rt < 2; ++rt) af[rt] = *(const LAS bf16x8*)(Ag + (32 * th + 16 * rt + fr) * PG + ks * 32 + fq * 8);
; #pragma unroll
;         for (int ct = 0; ct < 4; ++ct) { const bf16x8 bg = *(const bf16x8*)(g2T + (size_t)(hd * 64 + ct * 16 + fr) * 192 + ks * 32 + fq * 8);
; #pragma unroll
;             for (int rt = 0; rt < 2; ++rt) accg[ct][rt] = mma16(bg, af[rt], accg[ct][rt]); }
;     }
;     const bf16* Rr = (const bf16*)(ws + WS_RR); const bf16* Rk = (const bf16*)(ws + WS_RK); const bf16* Rv = (const bf16*)(ws + WS_RV);
;     const float* rkw = a->in[I_RK] + l * 256; const float* lnw = a->in[I_RLNW] + l * 256; const float* lnb = a->in[I_RLNB] + l * 256;
.LBB0_980:
	s_or_b64 exec, exec, s[6:7]
	v_and_b32_e32 v0, 15, v5
	v_readlane_b32 s6, v254, 32
	v_lshrrev_b32_e32 v1, 1, v5
	v_bfe_u32 v60, v5, 4, 2
	s_add_u32 s6, s4, s6
	v_and_or_b32 v61, v1, 32, v0
	v_ashrrev_i32_e32 v1, 1, v5
	s_addc_u32 s7, s5, 0
	v_lshlrev_b32_e32 v192, 4, v60
	v_and_b32_e32 v62, 0xffffffc0, v1
	v_or_b32_e32 v34, v62, v0
	v_lshl_add_u64 v[0:1], s[6:7], 0, v[192:193]
	s_mov_b64 s[6:7], 0x310000
	v_lshl_add_u64 v[32:33], v[0:1], 0, s[6:7]
	s_movk_i32 s8, 0x180
	v_mul_u32_u24_e32 v0, 0x150, v61
	v_mad_i64_i32 v[52:53], s[6:7], v34, s8, v[32:33]
	v_or_b32_e32 v16, 16, v34
	v_or_b32_e32 v24, 32, v34
	v_or_b32_e32 v34, 48, v34
	v_add3_u32 v48, 0, v192, v0
	v_mad_i64_i32 v[54:55], s[6:7], v16, s8, v[32:33]
	v_mad_i64_i32 v[56:57], s[6:7], v24, s8, v[32:33]
	v_mad_i64_i32 v[58:59], s[6:7], v34, s8, v[32:33]
	s_waitcnt lgkmcnt(0)
	s_barrier
	ds_read_b128 v[0:3], v48
	ds_read_b128 v[4:7], v48 offset:5376
	global_load_dwordx4 v[8:11], v[52:53], off
	global_load_dwordx4 v[16:19], v[54:55], off
	global_load_dwordx4 v[24:27], v[56:57], off
	global_load_dwordx4 v[32:35], v[58:59], off
	global_load_dwordx4 v[120:123], v[52:53], off offset:64
	global_load_dwordx4 v[124:127], v[54:55], off offset:64
	global_load_dwordx4 v[128:131], v[56:57], off offset:64
	global_load_dwordx4 v[132:135], v[58:59], off offset:64
	global_load_dwordx4 v[136:139], v[52:53], off offset:128
	global_load_dwordx4 v[140:143], v[54:55], off offset:128
	global_load_dwordx4 v[144:147], v[56:57], off offset:128
	global_load_dwordx4 v[148:151], v[58:59], off offset:128
	global_load_dwordx4 v[152:155], v[52:53], off offset:192
	global_load_dwordx4 v[156:159], v[54:55], off offset:192
	global_load_dwordx4 v[160:163], v[56:57], off offset:192
	global_load_dwordx4 v[164:167], v[58:59], off offset:192
	global_load_dwordx4 v[168:171], v[52:53], off offset:256
	global_load_dwordx4 v[172:175], v[54:55], off offset:256
	global_load_dwordx4 v[176:179], v[56:57], off offset:256
	global_load_dwordx4 v[180:183], v[58:59], off offset:256
	s_add_u32 s10, s4, 0x18000000
	s_addc_u32 s11, s5, 0
	s_add_u32 s8, s4, 0x19000000
	s_addc_u32 s9, s5, 0
	v_readlane_b32 s16, v254, 33
	s_add_u32 s6, s4, 0x1a000000
	v_readlane_b32 s17, v254, 34
	s_addc_u32 s7, s5, 0
	s_lshl_b64 s[22:23], s[16:17], 2
	s_waitcnt vmcnt(19) lgkmcnt(1)
	v_mfma_f32_16x16x32_bf16 v[12:15], v[8:11], v[0:3], 0
	s_waitcnt lgkmcnt(0)
	v_mfma_f32_16x16x32_bf16 v[8:11], v[8:11], v[4:7], 0
	s_waitcnt vmcnt(18)
	v_mfma_f32_16x16x32_bf16 v[20:23], v[16:19], v[0:3], 0
	v_mfma_f32_16x16x32_bf16 v[16:19], v[16:19], v[4:7], 0
	s_waitcnt vmcnt(17)
	v_mfma_f32_16x16x32_bf16 v[28:31], v[24:27], v[0:3], 0
	v_mfma_f32_16x16x32_bf16 v[24:27], v[24:27], v[4:7], 0
	s_waitcnt vmcnt(16)
	v_mfma_f32_16x16x32_bf16 v[0:3], v[32:35], v[0:3], 0
	v_mfma_f32_16x16x32_bf16 v[4:7], v[32:35], v[4:7], 0
	ds_read_b128 v[32:35], v48 offset:64
	ds_read_b128 v[36:39], v48 offset:5440
	s_waitcnt vmcnt(0) lgkmcnt(1)
	v_mfma_f32_16x16x32_bf16 v[12:15], v[120:123], v[32:35], v[12:15]
	s_waitcnt lgkmcnt(0)
	v_mfma_f32_16x16x32_bf16 v[8:11], v[120:123], v[36:39], v[8:11]
	v_mfma_f32_16x16x32_bf16 v[20:23], v[124:127], v[32:35], v[20:23]
	v_mfma_f32_16x16x32_bf16 v[16:19], v[124:127], v[36:39], v[16:19]
	v_mfma_f32_16x16x32_bf16 v[28:31], v[128:131], v[32:35], v[28:31]
	v_mfma_f32_16x16x32_bf16 v[24:27], v[128:131], v[36:39], v[24:27]
	v_mfma_f32_16x16x32_bf16 v[0:3], v[132:135], v[32:35], v[0:3]
	v_mfma_f32_16x16x32_bf16 v[4:7], v[132:135], v[36:39], v[4:7]
	ds_read_b128 v[32:35], v48 offset:128
	ds_read_b128 v[36:39], v48 offset:5504
	s_waitcnt lgkmcnt(1)
	v_mfma_f32_16x16x32_bf16 v[12:15], v[136:139], v[32:35], v[12:15]
	s_waitcnt lgkmcnt(0)
	v_mfma_f32_16x16x32_bf16 v[8:11], v[136:139], v[36:39], v[8:11]
	v_mfma_f32_16x16x32_bf16 v[20:23], v[140:143], v[32:35], v[20:23]
	v_mfma_f32_16x16x32_bf16 v[16:19], v[140:143], v[36:39], v[16:19]
	v_mfma_f32_16x16x32_bf16 v[28:31], v[144:147], v[32:35], v[28:31]
	v_mfma_f32_16x16x32_bf16 v[24:27], v[144:147], v[36:39], v[24:27]
	v_mfma_f32_16x16x32_bf16 v[0:3], v[148:151], v[32:35], v[0:3]
	v_mfma_f32_16x16x32_bf16 v[4:7], v[148:151], v[36:39], v[4:7]
	ds_read_b128 v[32:35], v48 offset:192
	ds_read_b128 v[36:39], v48 offset:5568
	s_waitcnt lgkmcnt(1)
	v_mfma_f32_16x16x32_bf16 v[12:15], v[152:155], v[32:35], v[12:15]
	s_waitcnt lgkmcnt(0)
	v_mfma_f32_16x16x32_bf16 v[8:11], v[152:155], v[36:39], v[8:11]
	v_mfma_f32_16x16x32_bf16 v[20:23], v[156:159], v[32:35], v[20:23]
	v_mfma_f32_16x16x32_bf16 v[16:19], v[156:159], v[36:39], v[16:19]
	v_mfma_f32_16x16x32_bf16 v[44:47], v[160:163], v[32:35], v[28:31]
	v_mfma_f32_16x16x32_bf16 v[40:43], v[160:163], v[36:39], v[24:27]
	s_nop 2
	v_mfma_f32_16x16x32_bf16 v[0:3], v[164:167], v[32:35], v[0:3]
	v_mfma_f32_16x16x32_bf16 v[32:35], v[164:167], v[36:39], v[4:7]
	ds_read_b128 v[36:39], v48 offset:256
	ds_read_b128 v[48:51], v48 offset:5632
	s_nop 0
	s_waitcnt lgkmcnt(1)
	v_mfma_f32_16x16x32_bf16 v[28:31], v[168:171], v[36:39], v[12:15]
	s_waitcnt lgkmcnt(0)
	v_mfma_f32_16x16x32_bf16 v[12:15], v[168:171], v[48:51], v[8:11]
	v_mov_b64_e32 v[54:55], s[0:1]
	v_mfma_f32_16x16x32_bf16 v[24:27], v[172:175], v[36:39], v[20:23]
	v_mfma_f32_16x16x32_bf16 v[8:11], v[172:175], v[48:51], v[16:19]
	v_mfma_f32_16x16x32_bf16 v[20:23], v[176:179], v[36:39], v[44:47]
	v_mfma_f32_16x16x32_bf16 v[4:7], v[176:179], v[48:51], v[40:43]
	s_nop 2
	v_mfma_f32_16x16x32_bf16 v[16:19], v[180:183], v[36:39], v[0:3]
	s_load_dwordx4 s[12:15], s[2:3], 0x90
	s_load_dwordx2 s[20:21], s[2:3], 0xa0
	s_waitcnt lgkmcnt(0)
; DI void rwkv_post_item(KA a, const int l, LAS unsigned char* lds, const int tile) {
;     ...
;     for (int rt = 0; rt < 2; ++rt) { const int tk = t0 + 32 * th + 16 * rt + fr;
;         float y[4][4], sy = 0.f, srk = 0.f;
; #pragma unroll
;         for (int ct = 0; ct < 4; ++ct) { const int c4 = hd * 64 + ct * 16 + 4 * fq; const size_t ro = (size_t)tk * 256 + c4; const f32x4 rk4 = *(const f32x4*)(rkw + c4);
;             const v2u yy = *(const v2u*)(H + (size_t)tk * HP + C_RR + c4), r2 = *(const v2u*)(Rr + ro), k2 = *(const v2u*)(Rk + ro);
;             const float y_[4] = {bflo(yy.x), bfhi(yy.x), bflo(yy.y), bfhi(yy.y)}, r_[4] = {bflo(r2.x), bfhi(r2.x), bflo(r2.y), bfhi(r2.y)}, k_[4] = {bflo(k2.x), bfhi(k2.x), bflo(k2.y), bfhi(k2.y)};
; #pragma unroll
;             for (int j = 0; j < 4; ++j) { y[ct][j] = y_[j]; sy += y_[j]; srk += r_[j] * k_[j] * rk4[j]; } }
	s_add_u32 s16, s12, s22
	v_mfma_f32_16x16x32_bf16 v[0:3], v[180:183], v[48:51], v[32:35]
	v_or_b32_e32 v50, s19, v61
	v_lshl_or_b32 v48, v60, 2, v62
	v_ashrrev_i32_e32 v51, 31, v50
	v_and_b32_e32 v33, 64, v238
	v_xor_b32_e32 v32, 16, v238
	v_add_u32_e32 v33, 64, v33
	v_cmp_lt_i32_e32 vcc, v32, v33
	s_movk_i32 s19, 0x1c00
	v_ashrrev_i32_e32 v49, 31, v48
	v_cndmask_b32_e32 v32, v238, v32, vcc
	v_lshlrev_b32_e32 v76, 2, v32
	v_xor_b32_e32 v32, 32, v238
	v_cmp_lt_i32_e32 vcc, v32, v33
	v_mad_i64_i32 v[34:35], s[0:1], v50, s19, v[54:55]
	s_nop 0
	v_cndmask_b32_e32 v32, v238, v32, vcc
	v_lshlrev_b32_e32 v67, 2, v32
	v_lshlrev_b64 v[32:33], 8, v[50:51]
	v_lshl_add_u64 v[56:57], v[32:33], 0, v[48:49]
	v_lshlrev_b64 v[40:41], 1, v[48:49]
	v_lshl_add_u64 v[38:39], v[34:35], 0, v[40:41]
	v_lshlrev_b64 v[34:35], 1, v[56:57]
	v_lshl_add_u64 v[56:57], s[10:11], 0, v[34:35]
	v_lshl_add_u64 v[34:35], s[8:9], 0, v[34:35]
	s_addc_u32 s17, s13, s23
	v_lshlrev_b64 v[36:37], 2, v[48:49]
	global_load_dwordx2 v[52:53], v[38:39], off offset:2080
	v_lshl_add_u64 v[42:43], s[16:17], 0, v[36:37]
	global_load_dwordx2 v[56:57], v[56:57], off
	s_add_u32 s12, s14, s22
	global_load_dwordx2 v[34:35], v[34:35], off
	s_addc_u32 s13, s15, s23
	global_load_dwordx4 v[44:47], v[42:43], off
	s_add_u32 s14, s20, s22
	s_addc_u32 s15, s21, s23
	s_mov_b64 s[16:17], 0x4000200
	s_add_i32 s18, s18, s76
	s_cmpk_lt_i32 s18, 0x200
	v_or_b32_e32 v152, 16, v48
	v_ashrrev_i32_e32 v153, 31, v152
	v_lshl_add_u64 v[154:155], v[32:33], 0, v[152:153]
	v_lshlrev_b64 v[154:155], 1, v[154:155]
	v_lshl_add_u64 v[156:157], s[10:11], 0, v[154:155]
	v_lshl_add_u64 v[154:155], s[8:9], 0, v[154:155]
	global_load_dwordx4 v[158:161], v[42:43], off offset:64
	global_load_dwordx2 v[162:163], v[38:39], off offset:2112
	global_load_dwordx2 v[156:157], v[156:157], off
	global_load_dwordx2 v[154:155], v[154:155], off
	v_or_b32_e32 v164, 32, v48
	v_ashrrev_i32_e32 v165, 31, v164
	v_lshl_add_u64 v[166:167], v[32:33], 0, v[164:165]
	v_lshlrev_b64 v[166:167], 1, v[166:167]
	v_lshl_add_u64 v[168:169], s[10:11], 0, v[166:167]
	v_lshl_add_u64 v[166:167], s[8:9], 0, v[166:167]
	global_load_dwordx4 v[170:173], v[42:43], off offset:128
	global_load_dwordx2 v[174:175], v[38:39], off offset:2144
	global_load_dwordx2 v[168:169], v[168:169], off
	global_load_dwordx2 v[166:167], v[166:167], off
	v_or_b32_e32 v176, 48, v48
	v_ashrrev_i32_e32 v177, 31, v176
	v_lshl_add_u64 v[178:179], v[32:33], 0, v[176:177]
	global_load_dwordx4 v[180:183], v[42:43], off offset:192
	global_load_dwordx2 v[184:185], v[38:39], off offset:2176
	v_lshlrev_b64 v[186:187], 1, v[178:179]
	v_lshl_add_u64 v[188:189], s[10:11], 0, v[186:187]
	global_load_dwordx2 v[188:189], v[188:189], off
	s_waitcnt vmcnt(3)
	v_lshlrev_b32_e32 v82, 16, v52
	v_and_b32_e32 v83, 0xffff0000, v52
	s_waitcnt vmcnt(2)
	v_lshlrev_b32_e32 v58, 16, v56
	v_and_b32_e32 v56, 0xffff0000, v56
	s_waitcnt vmcnt(1)
	v_lshlrev_b32_e32 v60, 16, v34
	v_and_b32_e32 v34, 0xffff0000, v34
	v_mul_f32_e32 v58, v58, v60
	v_lshlrev_b32_e32 v59, 16, v57
	v_lshlrev_b32_e32 v61, 16, v35
	s_waitcnt vmcnt(0)
	v_fma_f32 v60, v44, v58, 0
	v_mul_f32_e32 v34, v56, v34
	v_and_b32_e32 v57, 0xffff0000, v57
	v_and_b32_e32 v35, 0xffff0000, v35
	v_fmac_f32_e32 v60, v45, v34
	v_mul_f32_e32 v34, v59, v61
	v_fmac_f32_e32 v60, v46, v34
	v_mul_f32_e32 v34, v57, v35
	v_fmac_f32_e32 v60, v47, v34
	v_lshlrev_b32_e32 v80, 16, v53
	v_and_b32_e32 v81, 0xffff0000, v53
	s_waitcnt vmcnt(2)
	v_lshlrev_b32_e32 v94, 16, v162
	v_and_b32_e32 v95, 0xffff0000, v162
	s_waitcnt vmcnt(1)
	v_lshlrev_b32_e32 v61, 16, v156
	v_and_b32_e32 v58, 0xffff0000, v156
	s_waitcnt vmcnt(0)
	v_lshlrev_b32_e32 v64, 16, v154
	v_and_b32_e32 v34, 0xffff0000, v154
	v_mul_f32_e32 v61, v61, v64
	v_fmac_f32_e32 v60, v158, v61
	v_mul_f32_e32 v34, v58, v34
	v_fmac_f32_e32 v60, v159, v34
	v_and_b32_e32 v45, 0xffff0000, v157
	v_lshlrev_b32_e32 v44, 16, v157
	v_and_b32_e32 v59, 0xffff0000, v155
	v_lshlrev_b32_e32 v58, 16, v155
	v_pk_mul_f32 v[34:35], v[44:45], v[58:59]
	v_pk_mul_f32 v[34:35], v[160:161], v[34:35]
	v_add_f32_e32 v34, v34, v60
	v_add_f32_e32 v66, v35, v34
	v_lshlrev_b32_e32 v90, 16, v163
	v_and_b32_e32 v91, 0xffff0000, v163
	s_waitcnt vmcnt(2)
	v_lshlrev_b32_e32 v62, 16, v174
	v_and_b32_e32 v63, 0xffff0000, v174
	s_waitcnt vmcnt(1)
	v_and_b32_e32 v69, 0xffff0000, v168
	v_lshlrev_b32_e32 v68, 16, v168
	s_waitcnt vmcnt(0)
	v_and_b32_e32 v71, 0xffff0000, v166
	v_lshlrev_b32_e32 v70, 16, v166
	v_pk_mul_f32 v[68:69], v[68:69], v[70:71]
	v_lshlrev_b32_e32 v60, 16, v167
	v_pk_mul_f32 v[44:45], v[170:171], v[68:69]
	s_nop 0
	v_add_f32_e32 v34, v66, v44
	v_add_f32_e32 v66, v45, v34
	v_and_b32_e32 v45, 0xffff0000, v169
	v_lshlrev_b32_e32 v44, 16, v169
	v_and_b32_e32 v61, 0xffff0000, v167
	v_pk_mul_f32 v[34:35], v[44:45], v[60:61]
	v_pk_mul_f32 v[34:35], v[172:173], v[34:35]
	v_add_f32_e32 v34, v34, v66
	v_add_f32_e32 v66, v35, v34
	v_lshl_add_u64 v[38:39], s[8:9], 0, v[186:187]
	s_waitcnt vmcnt(1)
	v_and_b32_e32 v86, 0xffff0000, v184
	global_load_dwordx2 v[38:39], v[38:39], off
	v_lshlrev_b32_e32 v87, 16, v184
	v_and_b32_e32 v72, 0xffff0000, v175
	s_waitcnt vmcnt(1)
	v_and_b32_e32 v47, 0xffff0000, v188
	v_lshlrev_b32_e32 v46, 16, v188
	s_waitcnt vmcnt(0)
	v_and_b32_e32 v69, 0xffff0000, v38
	v_lshlrev_b32_e32 v68, 16, v38
	v_pk_mul_f32 v[46:47], v[46:47], v[68:69]
	v_lshlrev_b32_e32 v44, 16, v39
	v_pk_mul_f32 v[32:33], v[180:181], v[46:47]
	v_lshl_add_u64 v[46:47], s[14:15], 0, v[36:37]
	v_add_f32_e32 v32, v66, v32
	v_add_f32_e32 v38, v33, v32
	v_and_b32_e32 v33, 0xffff0000, v189
	v_lshlrev_b32_e32 v32, 16, v189
	v_and_b32_e32 v45, 0xffff0000, v39
	v_pk_mul_f32 v[32:33], v[32:33], v[44:45]
	v_lshl_add_u64 v[44:45], s[12:13], 0, v[36:37]
	v_pk_mul_f32 v[32:33], v[182:183], v[32:33]
	s_mov_b32 s12, 0xf800000
	v_add_f32_e32 v32, v32, v38
	v_add_f32_e32 v32, v33, v32
	ds_bpermute_b32 v33, v76, v32
	global_load_dwordx4 v[36:39], v[46:47], off
	s_waitcnt lgkmcnt(0)
; DI unsigned pk2(float lo, float hi) { const f32x2 v = {lo, hi}; const bf16x2_t b = __builtin_convertvector(v, bf16x2_t); return __builtin_bit_cast(unsigned, b); }
; DI void rwkv_post_item(KA a, const int l, LAS unsigned char* lds, const int tile) {
;     ...
;         sy += __shfl_xor(sy, 16); sy += __shfl_xor(sy, 32); srk += __shfl_xor(srk, 16); srk += __shfl_xor(srk, 32);
;         const float mean = sy * (1.f / 64.f); float q = 0.f;
; #pragma unroll
;         for (int ct = 0; ct < 4; ++ct)
; #pragma unroll
;             for (int j = 0; j < 4; ++j) { const float d = y[ct][j] - mean; q += d * d; }
;         q += __shfl_xor(q, 16); q += __shfl_xor(q, 32);
;         const float rstd = 1.f / sqrtf(q * (1.f / 64.f) + 64e-5f);
; #pragma unroll
;         for (int ct = 0; ct < 4; ++ct) { const int c4 = hd * 64 + ct * 16 + 4 * fq; const size_t ro = (size_t)tk * 256 + c4; const f32x4 lw = *(const f32x4*)(lnw + c4), lb = *(const f32x4*)(lnb + c4);
;             const v2u v2 = *(const v2u*)(Rv + ro); const float v_[4] = {bflo(v2.x), bfhi(v2.x), bflo(v2.y), bfhi(v2.y)}; float o[4];
; #pragma unroll
;             for (int j = 0; j < 4; ++j) o[j] = ((y[ct][j] - mean) * rstd * lw[j] + lb[j] + srk * v_[j]) * accg[ct][rt][j];
;             v2u p; p.x = pk2(o[0], o[1]); p.y = pk2(o[2], o[3]); *(v2u*)(act + (size_t)tk * D + 256 + c4) = p; }
	v_add_f32_e32 v32, v32, v33
	ds_bpermute_b32 v33, v67, v32
	s_waitcnt lgkmcnt(0)
	v_add_f32_e32 v66, v32, v33
	v_lshlrev_b64 v[32:33], 9, v[50:51]
	v_lshl_add_u64 v[70:71], s[6:7], 0, v[32:33]
	v_lshl_add_u64 v[70:71], v[70:71], 0, v[40:41]
	global_load_dwordx2 v[78:79], v[70:71], off
	global_load_dwordx2 v[52:53], v[70:71], off offset:32
	global_load_dwordx2 v[100:101], v[70:71], off offset:64
	v_lshlrev_b64 v[32:33], 11, v[50:51]
	v_add_f32_e32 v51, 0, v82
	v_add_f32_e32 v51, v51, v83
	v_add_f32_e32 v51, v51, v80
	v_add_f32_e32 v51, v51, v81
	v_add_f32_e32 v51, v51, v94
	v_add_f32_e32 v51, v51, v95
	v_add_f32_e32 v51, v51, v90
	v_lshl_add_u64 v[32:33], s[4:5], 0, v[32:33]
	v_add_f32_e32 v51, v51, v91
	v_lshl_add_u64 v[68:69], v[32:33], 0, s[16:17]
	global_load_dwordx4 v[32:35], v[44:45], off
	global_load_dwordx4 v[128:131], v[44:45], off offset:64
	global_load_dwordx4 v[132:135], v[46:47], off offset:64
	global_load_dwordx4 v[136:139], v[44:45], off offset:128
	global_load_dwordx4 v[140:143], v[46:47], off offset:128
	global_load_dwordx4 v[144:147], v[44:45], off offset:192
	global_load_dwordx4 v[148:151], v[46:47], off offset:192
	v_add_f32_e32 v51, v51, v62
	v_add_f32_e32 v51, v51, v63
	v_lshl_add_u64 v[88:89], v[68:69], 0, v[40:41]
	s_waitcnt vmcnt(3)
	v_lshlrev_b32_e32 v74, 16, v79
	v_and_b32_e32 v75, 0xffff0000, v79
	v_lshlrev_b32_e32 v84, 16, v78
	v_and_b32_e32 v85, 0xffff0000, v78
	v_and_b32_e32 v78, 0xffff0000, v185
	v_lshlrev_b32_e32 v79, 16, v185
	v_lshlrev_b32_e32 v73, 16, v175
	v_add_f32_e32 v51, v51, v73
	v_add_f32_e32 v51, v51, v72
	v_add_f32_e32 v51, v51, v87
	v_add_f32_e32 v51, v51, v86
	v_add_f32_e32 v51, v51, v79
	v_add_f32_e32 v51, v51, v78
	ds_bpermute_b32 v64, v76, v51
	s_waitcnt vmcnt(2)
	v_lshlrev_b32_e32 v96, 16, v52
	v_and_b32_e32 v97, 0xffff0000, v52
	v_lshlrev_b32_e32 v92, 16, v53
	v_and_b32_e32 v93, 0xffff0000, v53
	s_waitcnt lgkmcnt(0)
	v_add_f32_e32 v51, v51, v64
	ds_bpermute_b32 v64, v67, v51
	v_lshlrev_b64 v[52:53], 1, v[152:153]
	v_lshl_add_u64 v[98:99], v[68:69], 0, v[52:53]
	s_waitcnt lgkmcnt(0)
	v_add_f32_e32 v51, v51, v64
	v_mul_f32_e32 v102, 0x3c800000, v51
	v_pk_add_f32 v[82:83], v[82:83], v[102:103] op_sel_hi:[1,0] neg_lo:[0,1] neg_hi:[0,1]
	v_pk_add_f32 v[80:81], v[80:81], v[102:103] op_sel_hi:[1,0] neg_lo:[0,1] neg_hi:[0,1]
	v_pk_mul_f32 v[104:105], v[82:83], v[82:83]
	v_pk_mul_f32 v[106:107], v[80:81], v[80:81]
	v_add_f32_e32 v51, v104, v105
	v_pk_add_f32 v[94:95], v[94:95], v[102:103] op_sel_hi:[1,0] neg_lo:[0,1] neg_hi:[0,1]
	v_add_f32_e32 v51, v106, v51
	v_pk_mul_f32 v[108:109], v[94:95], v[94:95]
	v_add_f32_e32 v51, v107, v51
	v_pk_add_f32 v[90:91], v[90:91], v[102:103] op_sel_hi:[1,0] neg_lo:[0,1] neg_hi:[0,1]
	v_add_f32_e32 v51, v108, v51
	v_pk_mul_f32 v[110:111], v[90:91], v[90:91]
	v_add_f32_e32 v51, v109, v51
	v_pk_add_f32 v[112:113], v[62:63], v[102:103] op_sel_hi:[1,0] neg_lo:[0,1] neg_hi:[0,1]
	v_add_f32_e32 v51, v110, v51
	v_pk_mul_f32 v[114:115], v[112:113], v[112:113]
	v_add_f32_e32 v51, v111, v51
	v_pk_add_f32 v[116:117], v[72:73], v[102:103] op_sel_hi:[1,0] neg_lo:[0,1] neg_hi:[0,1]
	v_add_f32_e32 v51, v114, v51
	v_pk_mul_f32 v[72:73], v[116:117], v[116:117]
	v_add_f32_e32 v51, v115, v51
	v_pk_add_f32 v[64:65], v[86:87], v[102:103] op_sel_hi:[1,0] neg_lo:[0,1] neg_hi:[0,1]
	v_add_f32_e32 v51, v73, v51
	v_pk_mul_f32 v[86:87], v[64:65], v[64:65]
	v_add_f32_e32 v51, v72, v51
	v_pk_add_f32 v[62:63], v[78:79], v[102:103] op_sel_hi:[1,0] neg_lo:[0,1] neg_hi:[0,1]
	v_add_f32_e32 v51, v87, v51
	v_pk_mul_f32 v[78:79], v[62:63], v[62:63]
	v_add_f32_e32 v51, v86, v51
	v_add_f32_e32 v51, v79, v51
	v_add_f32_e32 v51, v78, v51
	ds_bpermute_b32 v72, v76, v51
	s_waitcnt lgkmcnt(0)
	v_add_f32_e32 v51, v51, v72
	ds_bpermute_b32 v72, v67, v51
	s_waitcnt lgkmcnt(0)
	v_add_f32_e32 v51, v51, v72
	v_fmamk_f32 v51, v51, 0x3c800000, v236
	v_cmp_gt_f32_e32 vcc, s12, v51
	v_mul_f32_e32 v72, 0x4f800000, v51
	s_nop 0
	v_cndmask_b32_e32 v51, v51, v72, vcc
	v_sqrt_f32_e32 v72, v51
	s_nop 0
	v_add_u32_e32 v73, -1, v72
	v_fma_f32 v77, -v73, v72, v51
	v_cmp_ge_f32_e64 s[0:1], 0, v77
	v_add_u32_e32 v77, 1, v72
	s_nop 0
	v_cndmask_b32_e64 v73, v72, v73, s[0:1]
	v_fma_f32 v72, -v77, v72, v51
	v_cmp_lt_f32_e64 s[0:1], 0, v72
	s_nop 1
	v_cndmask_b32_e64 v72, v73, v77, s[0:1]
	v_mul_f32_e32 v73, 0x37800000, v72
	v_cndmask_b32_e32 v72, v72, v73, vcc
	v_cmp_class_f32_e32 vcc, v51, v234
	s_nop 1
	v_cndmask_b32_e32 v51, v72, v51, vcc
	v_div_scale_f32 v72, s[0:1], v51, v51, 1.0
	v_rcp_f32_e32 v73, v72
	s_nop 0
	v_fma_f32 v77, -v72, v73, 1.0
	v_fmac_f32_e32 v73, v77, v73
	v_div_scale_f32 v77, vcc, 1.0, v51, 1.0
	v_mul_f32_e32 v78, v77, v73
	v_fma_f32 v79, -v72, v78, v77
	v_fmac_f32_e32 v78, v79, v73
	v_fma_f32 v72, -v72, v78, v77
	v_div_fmas_f32 v72, v72, v73, v78
	v_div_fixup_f32 v72, v72, v51, 1.0
	v_pk_mul_f32 v[78:79], v[82:83], v[72:73] op_sel_hi:[1,0]
	s_waitcnt vmcnt(0)
	v_pk_fma_f32 v[32:33], v[32:33], v[78:79], v[36:37]
	v_pk_mul_f32 v[36:37], v[94:95], v[72:73] op_sel_hi:[1,0]
	v_pk_fma_f32 v[32:33], v[66:67], v[84:85], v[32:33] op_sel_hi:[0,1,1]
	v_pk_mul_f32 v[28:29], v[28:29], v[32:33]
	v_pk_mul_f32 v[32:33], v[80:81], v[72:73] op_sel_hi:[1,0]
	v_cvt_pk_bf16_f32 v28, v28, v29
	v_pk_fma_f32 v[32:33], v[34:35], v[32:33], v[38:39]
	s_nop 0
	v_pk_fma_f32 v[32:33], v[66:67], v[74:75], v[32:33] op_sel_hi:[0,1,1]
	v_pk_mul_f32 v[30:31], v[30:31], v[32:33]
	s_nop 0
	v_cvt_pk_bf16_f32 v29, v30, v31
	global_store_dwordx2 v[88:89], v[28:29], off
	s_nop 0
	s_waitcnt vmcnt(1)
; DI unsigned pk2(float lo, float hi) { const f32x2 v = {lo, hi}; const bf16x2_t b = __builtin_convertvector(v, bf16x2_t); return __builtin_bit_cast(unsigned, b); }
; DI void rwkv_post_item(KA a, const int l, LAS unsigned char* lds, const int tile) {
;     ...
;     for (int rt = 0; rt < 2; ++rt) { const int tk = t0 + 32 * th + 16 * rt + fr;
;         float y[4][4], sy = 0.f, srk = 0.f;
; #pragma unroll
;         for (int ct = 0; ct < 4; ++ct) { const int c4 = hd * 64 + ct * 16 + 4 * fq; const size_t ro = (size_t)tk * 256 + c4; const f32x4 rk4 = *(const f32x4*)(rkw + c4);
;             const v2u yy = *(const v2u*)(H + (size_t)tk * HP + C_RR + c4), r2 = *(const v2u*)(Rr + ro), k2 = *(const v2u*)(Rk + ro);
;             const float y_[4] = {bflo(yy.x), bfhi(yy.x), bflo(yy.y), bfhi(yy.y)}, r_[4] = {bflo(r2.x), bfhi(r2.x), bflo(r2.y), bfhi(r2.y)}, k_[4] = {bflo(k2.x), bfhi(k2.x), bflo(k2.y), bfhi(k2.y)};
; #pragma unroll
;             for (int j = 0; j < 4; ++j) { y[ct][j] = y_[j]; sy += y_[j]; srk += r_[j] * k_[j] * rk4[j]; } }
;     ...
;         for (int ct = 0; ct < 4; ++ct) { const int c4 = hd * 64 + ct * 16 + 4 * fq; const size_t ro = (size_t)tk * 256 + c4; const f32x4 lw = *(const f32x4*)(lnw + c4), lb = *(const f32x4*)(lnb + c4);
;             const v2u v2 = *(const v2u*)(Rv + ro); const float v_[4] = {bflo(v2.x), bfhi(v2.x), bflo(v2.y), bfhi(v2.y)}; float o[4];
; #pragma unroll
;             for (int j = 0; j < 4; ++j) o[j] = ((y[ct][j] - mean) * rstd * lw[j] + lb[j] + srk * v_[j]) * accg[ct][rt][j];
;             v2u p; p.x = pk2(o[0], o[1]); p.y = pk2(o[2], o[3]); *(v2u*)(act + (size_t)tk * D + 256 + c4) = p; }
	v_pk_fma_f32 v[28:29], v[128:129], v[36:37], v[132:133]
	s_nop 0
	v_pk_fma_f32 v[28:29], v[66:67], v[96:97], v[28:29] op_sel_hi:[0,1,1]
	v_pk_mul_f32 v[24:25], v[24:25], v[28:29]
	v_pk_mul_f32 v[28:29], v[90:91], v[72:73] op_sel_hi:[1,0]
	v_cvt_pk_bf16_f32 v24, v24, v25
	v_pk_fma_f32 v[28:29], v[130:131], v[28:29], v[134:135]
	v_pk_mul_f32 v[34:35], v[112:113], v[72:73] op_sel_hi:[1,0]
	v_pk_fma_f32 v[28:29], v[66:67], v[92:93], v[28:29] op_sel_hi:[0,1,1]
	v_pk_mul_f32 v[26:27], v[26:27], v[28:29]
	v_lshlrev_b32_e32 v32, 16, v100
	v_cvt_pk_bf16_f32 v25, v26, v27
	global_store_dwordx2 v[98:99], v[24:25], off
	s_nop 0
	v_and_b32_e32 v33, 0xffff0000, v100
	s_waitcnt vmcnt(1)
	v_pk_fma_f32 v[24:25], v[136:137], v[34:35], v[140:141]
	s_nop 0
	v_pk_fma_f32 v[24:25], v[66:67], v[32:33], v[24:25] op_sel_hi:[0,1,1]
	v_pk_mul_f32 v[28:29], v[116:117], v[72:73] op_sel_hi:[1,0]
	v_pk_mul_f32 v[20:21], v[20:21], v[24:25]
	v_lshlrev_b32_e32 v24, 16, v101
	v_and_b32_e32 v25, 0xffff0000, v101
	v_pk_fma_f32 v[26:27], v[138:139], v[28:29], v[142:143] op_sel:[0,1,0] op_sel_hi:[1,0,1]
	v_lshlrev_b64 v[28:29], 1, v[164:165]
	v_pk_fma_f32 v[24:25], v[66:67], v[24:25], v[26:27] op_sel_hi:[0,1,1]
	v_pk_mul_f32 v[22:23], v[22:23], v[24:25]
	v_cvt_pk_bf16_f32 v20, v20, v21
	v_cvt_pk_bf16_f32 v21, v22, v23
	v_lshl_add_u64 v[22:23], v[68:69], 0, v[28:29]
	global_store_dwordx2 v[22:23], v[20:21], off
	s_nop 0
	global_load_dwordx2 v[30:31], v[70:71], off offset:96
	v_pk_mul_f32 v[34:35], v[64:65], v[72:73] op_sel_hi:[1,0]
	s_waitcnt vmcnt(0)
	v_lshlrev_b32_e32 v32, 16, v30
	v_and_b32_e32 v33, 0xffff0000, v30
	v_pk_fma_f32 v[20:21], v[144:145], v[34:35], v[148:149] op_sel:[0,1,0] op_sel_hi:[1,0,1]
	v_pk_mul_f32 v[24:25], v[62:63], v[72:73] op_sel_hi:[1,0]
	v_pk_fma_f32 v[20:21], v[66:67], v[32:33], v[20:21] op_sel_hi:[0,1,1]
	v_pk_mul_f32 v[16:17], v[16:17], v[20:21]
	v_lshlrev_b32_e32 v20, 16, v31
	v_and_b32_e32 v21, 0xffff0000, v31
	v_pk_fma_f32 v[22:23], v[146:147], v[24:25], v[150:151] op_sel:[0,1,0] op_sel_hi:[1,0,1]
	v_lshlrev_b64 v[24:25], 1, v[176:177]
	v_pk_fma_f32 v[20:21], v[66:67], v[20:21], v[22:23] op_sel_hi:[0,1,1]
	v_pk_mul_f32 v[18:19], v[18:19], v[20:21]
	v_cvt_pk_bf16_f32 v16, v16, v17
	v_cvt_pk_bf16_f32 v17, v18, v19
	v_lshl_add_u64 v[18:19], v[68:69], 0, v[24:25]
	global_store_dwordx2 v[18:19], v[16:17], off
	v_or_b32_e32 v16, 16, v50
	v_ashrrev_i32_e32 v17, 31, v16
	v_lshlrev_b64 v[18:19], 8, v[16:17]
	v_lshl_add_u64 v[22:23], v[18:19], 0, v[48:49]
	v_mad_i64_i32 v[20:21], s[0:1], v16, s19, v[54:55]
	v_lshlrev_b64 v[22:23], 1, v[22:23]
	v_lshl_add_u64 v[20:21], v[20:21], 0, v[40:41]
	v_lshl_add_u64 v[26:27], s[10:11], 0, v[22:23]
	v_lshl_add_u64 v[22:23], s[8:9], 0, v[22:23]
	global_load_dwordx2 v[32:33], v[20:21], off offset:2080
	global_load_dwordx4 v[34:37], v[42:43], off
	s_nop 0
	global_load_dwordx2 v[26:27], v[26:27], off
	s_nop 0
	global_load_dwordx2 v[22:23], v[22:23], off
	v_lshl_add_u64 v[128:129], v[18:19], 0, v[152:153]
	v_lshlrev_b64 v[128:129], 1, v[128:129]
	v_lshl_add_u64 v[130:131], s[10:11], 0, v[128:129]
	v_lshl_add_u64 v[128:129], s[8:9], 0, v[128:129]
	global_load_dwordx4 v[132:135], v[42:43], off offset:64
	global_load_dwordx2 v[136:137], v[20:21], off offset:2112
	global_load_dwordx2 v[130:131], v[130:131], off
	global_load_dwordx2 v[128:129], v[128:129], off
	v_lshl_add_u64 v[138:139], v[18:19], 0, v[164:165]
	v_lshlrev_b64 v[138:139], 1, v[138:139]
	v_lshl_add_u64 v[140:141], s[10:11], 0, v[138:139]
	v_lshl_add_u64 v[138:139], s[8:9], 0, v[138:139]
	global_load_dwordx4 v[142:145], v[42:43], off offset:128
	global_load_dwordx2 v[146:147], v[20:21], off offset:2144
	v_lshl_add_u64 v[148:149], v[18:19], 0, v[176:177]
	global_load_dwordx2 v[140:141], v[140:141], off
	v_lshlrev_b64 v[148:149], 1, v[148:149]
	global_load_dwordx2 v[138:139], v[138:139], off
	global_load_dwordx4 v[176:179], v[42:43], off offset:192
	global_load_dwordx2 v[150:151], v[20:21], off offset:2176
	v_lshl_add_u64 v[180:181], s[10:11], 0, v[148:149]
	v_lshl_add_u64 v[148:149], s[8:9], 0, v[148:149]
	global_load_dwordx2 v[180:181], v[180:181], off
	global_load_dwordx2 v[148:149], v[148:149], off
	s_waitcnt vmcnt(1)
	v_lshlrev_b32_e32 v30, 16, v26
	v_and_b32_e32 v26, 0xffff0000, v26
	s_waitcnt vmcnt(0)
	v_lshlrev_b32_e32 v38, 16, v22
	v_and_b32_e32 v22, 0xffff0000, v22
	v_mul_f32_e32 v30, v30, v38
	v_lshlrev_b32_e32 v31, 16, v27
	v_lshlrev_b32_e32 v39, 16, v23
	v_fma_f32 v48, v34, v30, 0
	v_mul_f32_e32 v22, v26, v22
	v_and_b32_e32 v27, 0xffff0000, v27
	v_and_b32_e32 v23, 0xffff0000, v23
	v_fmac_f32_e32 v48, v35, v22
	v_mul_f32_e32 v22, v31, v39
	v_fmac_f32_e32 v48, v36, v22
	v_mul_f32_e32 v22, v27, v23
	v_fmac_f32_e32 v48, v37, v22
	v_lshlrev_b32_e32 v56, 16, v32
	v_and_b32_e32 v57, 0xffff0000, v32
	s_waitcnt vmcnt(2)
	v_lshlrev_b32_e32 v68, 16, v136
	v_and_b32_e32 v69, 0xffff0000, v136
	s_waitcnt vmcnt(1)
	v_lshlrev_b32_e32 v30, 16, v130
	v_and_b32_e32 v26, 0xffff0000, v130
	s_waitcnt vmcnt(0)
	v_lshlrev_b32_e32 v31, 16, v128
	v_and_b32_e32 v22, 0xffff0000, v128
	v_mul_f32_e32 v30, v30, v31
	v_fmac_f32_e32 v48, v132, v30
	v_mul_f32_e32 v22, v26, v22
	v_and_b32_e32 v31, 0xffff0000, v131
	v_lshlrev_b32_e32 v30, 16, v131
	v_and_b32_e32 v27, 0xffff0000, v129
	v_lshlrev_b32_e32 v26, 16, v129
	v_fmac_f32_e32 v48, v133, v22
	v_pk_mul_f32 v[22:23], v[30:31], v[26:27]
	v_lshlrev_b32_e32 v62, 16, v137
	v_pk_mul_f32 v[22:23], v[134:135], v[22:23]
	v_and_b32_e32 v63, 0xffff0000, v137
	v_add_f32_e32 v22, v22, v48
	v_add_f32_e32 v54, v23, v22
	s_waitcnt vmcnt(2)
	v_lshlrev_b32_e32 v34, 16, v146
	v_and_b32_e32 v35, 0xffff0000, v146
	s_waitcnt vmcnt(1)
; DI void rwkv_post_item(KA a, const int l, LAS unsigned char* lds, const int tile) {
;     ...
;         for (int ct = 0; ct < 4; ++ct) { const int c4 = hd * 64 + ct * 16 + 4 * fq; const size_t ro = (size_t)tk * 256 + c4; const f32x4 rk4 = *(const f32x4*)(rkw + c4);
;             const v2u yy = *(const v2u*)(H + (size_t)tk * HP + C_RR + c4), r2 = *(const v2u*)(Rr + ro), k2 = *(const v2u*)(Rk + ro);
;             const float y_[4] = {bflo(yy.x), bfhi(yy.x), bflo(yy.y), bfhi(yy.y)}, r_[4] = {bflo(r2.x), bfhi(r2.x), bflo(r2.y), bfhi(r2.y)}, k_[4] = {bflo(k2.x), bfhi(k2.x), bflo(k2.y), bfhi(k2.y)};
; #pragma unroll
;             for (int j = 0; j < 4; ++j) { y[ct][j] = y_[j]; sy += y_[j]; srk += r_[j] * k_[j] * rk4[j]; } }
;         sy += __shfl_xor(sy, 16); sy += __shfl_xor(sy, 32); srk += __shfl_xor(srk, 16); srk += __shfl_xor(srk, 32);
;         const float mean = sy * (1.f / 64.f); float q = 0.f;
; #pragma unroll
;         for (int ct = 0; ct < 4; ++ct)
; #pragma unroll
;             for (int j = 0; j < 4; ++j) { const float d = y[ct][j] - mean; q += d * d; }
;         q += __shfl_xor(q, 16); q += __shfl_xor(q, 32);
;         const float rstd = 1.f / sqrtf(q * (1.f / 64.f) + 64e-5f);
	v_and_b32_e32 v31, 0xffff0000, v140
	v_lshlrev_b32_e32 v30, 16, v140
	s_waitcnt vmcnt(0)
	v_and_b32_e32 v37, 0xffff0000, v138
	v_lshlrev_b32_e32 v36, 16, v138
	v_pk_mul_f32 v[30:31], v[30:31], v[36:37]
	v_lshlrev_b32_e32 v26, 16, v139
	v_pk_mul_f32 v[30:31], v[142:143], v[30:31]
	s_nop 0
	v_add_f32_e32 v22, v54, v30
	v_add_f32_e32 v36, v31, v22
	v_and_b32_e32 v31, 0xffff0000, v141
	v_lshlrev_b32_e32 v30, 16, v141
	v_and_b32_e32 v27, 0xffff0000, v139
	v_pk_mul_f32 v[22:23], v[30:31], v[26:27]
	v_add_f32_e32 v31, 0, v56
	v_pk_mul_f32 v[22:23], v[144:145], v[22:23]
	s_nop 0
	v_add_f32_e32 v22, v22, v36
	v_add_f32_e32 v30, v23, v22
	v_add_f32_e32 v31, v31, v57
	s_waitcnt vmcnt(2)
	v_and_b32_e32 v32, 0xffff0000, v151
	s_waitcnt vmcnt(1)
	v_and_b32_e32 v23, 0xffff0000, v180
	v_lshlrev_b32_e32 v22, 16, v180
	s_waitcnt vmcnt(0)
	v_and_b32_e32 v27, 0xffff0000, v148
	v_lshlrev_b32_e32 v26, 16, v148
	v_pk_mul_f32 v[22:23], v[22:23], v[26:27]
	v_lshlrev_b32_e32 v20, 16, v149
	v_pk_mul_f32 v[22:23], v[176:177], v[22:23]
	v_lshlrev_b32_e32 v48, 16, v33
	v_add_f32_e32 v18, v30, v22
	v_add_f32_e32 v26, v23, v18
	v_and_b32_e32 v23, 0xffff0000, v181
	v_lshlrev_b32_e32 v22, 16, v181
	v_and_b32_e32 v21, 0xffff0000, v149
	v_pk_mul_f32 v[18:19], v[22:23], v[20:21]
	v_and_b32_e32 v49, 0xffff0000, v33
	v_pk_mul_f32 v[18:19], v[178:179], v[18:19]
	v_add_f32_e32 v31, v31, v48
	v_add_f32_e32 v18, v18, v26
	v_add_f32_e32 v18, v19, v18
	ds_bpermute_b32 v19, v76, v18
	v_add_f32_e32 v31, v31, v49
	v_add_f32_e32 v31, v31, v68
	v_add_f32_e32 v31, v31, v69
	v_add_f32_e32 v31, v31, v62
	s_waitcnt lgkmcnt(0)
	v_add_f32_e32 v18, v18, v19
	ds_bpermute_b32 v19, v67, v18
	v_add_f32_e32 v31, v31, v63
	v_add_f32_e32 v31, v31, v34
	v_lshlrev_b32_e32 v33, 16, v151
	v_lshlrev_b32_e32 v43, 16, v147
	s_waitcnt lgkmcnt(0)
	v_add_f32_e32 v30, v18, v19
	v_lshlrev_b64 v[18:19], 9, v[16:17]
	v_lshl_add_u64 v[36:37], s[6:7], 0, v[18:19]
	v_lshlrev_b64 v[16:17], 11, v[16:17]
	v_lshl_add_u64 v[16:17], s[4:5], 0, v[16:17]
	v_lshl_add_u64 v[36:37], v[36:37], 0, v[40:41]
	v_lshl_add_u64 v[26:27], v[16:17], 0, s[16:17]
	global_load_dwordx4 v[16:19], v[44:45], off
	global_load_dwordx4 v[20:23], v[46:47], off
	global_load_dwordx4 v[152:155], v[44:45], off offset:64
	global_load_dwordx4 v[156:159], v[46:47], off offset:64
	global_load_dwordx4 v[160:163], v[44:45], off offset:128
	global_load_dwordx4 v[164:167], v[46:47], off offset:128
	global_load_dwordx4 v[168:171], v[44:45], off offset:192
	global_load_dwordx4 v[172:175], v[46:47], off offset:192
	global_load_dwordx2 v[54:55], v[36:37], off
	global_load_dwordx2 v[60:61], v[36:37], off offset:32
	v_add_f32_e32 v31, v31, v35
	v_add_f32_e32 v31, v31, v43
	v_lshl_add_u64 v[40:41], v[26:27], 0, v[40:41]
	v_lshl_add_u64 v[52:53], v[26:27], 0, v[52:53]
	s_waitcnt vmcnt(1)
	v_lshlrev_b32_e32 v50, 16, v55
	v_and_b32_e32 v51, 0xffff0000, v55
	v_lshlrev_b32_e32 v58, 16, v54
	v_and_b32_e32 v59, 0xffff0000, v54
	v_and_b32_e32 v54, 0xffff0000, v150
	v_lshlrev_b32_e32 v55, 16, v150
	v_and_b32_e32 v42, 0xffff0000, v147
	v_add_f32_e32 v31, v31, v42
	v_add_f32_e32 v31, v31, v55
	v_add_f32_e32 v31, v31, v54
	v_add_f32_e32 v31, v31, v33
	v_add_f32_e32 v31, v31, v32
	ds_bpermute_b32 v38, v76, v31
	s_waitcnt vmcnt(0)
	v_lshlrev_b32_e32 v64, 16, v61
	v_and_b32_e32 v65, 0xffff0000, v61
	v_lshlrev_b32_e32 v70, 16, v60
	v_and_b32_e32 v71, 0xffff0000, v60
	s_waitcnt lgkmcnt(0)
	v_add_f32_e32 v31, v31, v38
	ds_bpermute_b32 v38, v67, v31
	global_load_dwordx2 v[60:61], v[36:37], off offset:64
	s_waitcnt lgkmcnt(0)
	v_add_f32_e32 v31, v31, v38
	v_mul_f32_e32 v38, 0x3c800000, v31
	v_mov_b32_e32 v39, v147
	v_pk_add_f32 v[56:57], v[56:57], v[38:39] op_sel_hi:[1,0] neg_lo:[0,1] neg_hi:[0,1]
	v_pk_add_f32 v[48:49], v[48:49], v[38:39] op_sel_hi:[1,0] neg_lo:[0,1] neg_hi:[0,1]
	v_pk_mul_f32 v[72:73], v[56:57], v[56:57]
	v_pk_mul_f32 v[74:75], v[48:49], v[48:49]
	v_add_f32_e32 v31, v72, v73
	v_pk_add_f32 v[68:69], v[68:69], v[38:39] op_sel_hi:[1,0] neg_lo:[0,1] neg_hi:[0,1]
	v_add_f32_e32 v31, v74, v31
	v_pk_mul_f32 v[78:79], v[68:69], v[68:69]
	v_add_f32_e32 v31, v75, v31
	v_pk_add_f32 v[62:63], v[62:63], v[38:39] op_sel_hi:[1,0] neg_lo:[0,1] neg_hi:[0,1]
	v_add_f32_e32 v31, v78, v31
	v_pk_mul_f32 v[80:81], v[62:63], v[62:63]
	v_add_f32_e32 v31, v79, v31
	v_pk_add_f32 v[82:83], v[34:35], v[38:39] op_sel_hi:[1,0] neg_lo:[0,1] neg_hi:[0,1]
	v_add_f32_e32 v31, v80, v31
	v_pk_mul_f32 v[84:85], v[82:83], v[82:83]
	v_add_f32_e32 v31, v81, v31
	v_pk_add_f32 v[42:43], v[42:43], v[38:39] op_sel_hi:[1,0] neg_lo:[0,1] neg_hi:[0,1]
	v_add_f32_e32 v31, v84, v31
	v_pk_mul_f32 v[86:87], v[42:43], v[42:43]
	v_add_f32_e32 v31, v85, v31
	v_pk_add_f32 v[34:35], v[54:55], v[38:39] op_sel_hi:[1,0] neg_lo:[0,1] neg_hi:[0,1]
	v_add_f32_e32 v31, v87, v31
	v_pk_mul_f32 v[54:55], v[34:35], v[34:35]
	v_add_f32_e32 v31, v86, v31
	v_pk_add_f32 v[32:33], v[32:33], v[38:39] op_sel_hi:[1,0] neg_lo:[0,1] neg_hi:[0,1]
	v_add_f32_e32 v31, v55, v31
	v_pk_mul_f32 v[38:39], v[32:33], v[32:33]
	v_add_f32_e32 v31, v54, v31
	v_add_f32_e32 v31, v39, v31
	v_add_f32_e32 v31, v38, v31
	ds_bpermute_b32 v38, v76, v31
	s_waitcnt lgkmcnt(0)
; DI unsigned pk2(float lo, float hi) { const f32x2 v = {lo, hi}; const bf16x2_t b = __builtin_convertvector(v, bf16x2_t); return __builtin_bit_cast(unsigned, b); }
; DI void rwkv_post_item(KA a, const int l, LAS unsigned char* lds, const int tile) {
;     ...
;         const float rstd = 1.f / sqrtf(q * (1.f / 64.f) + 64e-5f);
; #pragma unroll
;         for (int ct = 0; ct < 4; ++ct) { const int c4 = hd * 64 + ct * 16 + 4 * fq; const size_t ro = (size_t)tk * 256 + c4; const f32x4 lw = *(const f32x4*)(lnw + c4), lb = *(const f32x4*)(lnb + c4);
;             const v2u v2 = *(const v2u*)(Rv + ro); const float v_[4] = {bflo(v2.x), bfhi(v2.x), bflo(v2.y), bfhi(v2.y)}; float o[4];
; #pragma unroll
;             for (int j = 0; j < 4; ++j) o[j] = ((y[ct][j] - mean) * rstd * lw[j] + lb[j] + srk * v_[j]) * accg[ct][rt][j];
;             v2u p; p.x = pk2(o[0], o[1]); p.y = pk2(o[2], o[3]); *(v2u*)(act + (size_t)tk * D + 256 + c4) = p; }
	v_add_f32_e32 v31, v31, v38
	ds_bpermute_b32 v38, v67, v31
	s_waitcnt lgkmcnt(0)
	v_add_f32_e32 v31, v31, v38
	v_fmamk_f32 v31, v31, 0x3c800000, v236
	v_cmp_gt_f32_e32 vcc, s12, v31
	v_mul_f32_e32 v38, 0x4f800000, v31
	s_nop 0
	v_cndmask_b32_e32 v31, v31, v38, vcc
	v_sqrt_f32_e32 v38, v31
	s_nop 0
	v_add_u32_e32 v39, -1, v38
	v_fma_f32 v54, -v39, v38, v31
	v_cmp_ge_f32_e64 s[0:1], 0, v54
	v_add_u32_e32 v54, 1, v38
	s_nop 0
	v_cndmask_b32_e64 v39, v38, v39, s[0:1]
	v_fma_f32 v38, -v54, v38, v31
	v_cmp_lt_f32_e64 s[0:1], 0, v38
	s_nop 1
	v_cndmask_b32_e64 v38, v39, v54, s[0:1]
	v_mul_f32_e32 v39, 0x37800000, v38
	v_cndmask_b32_e32 v38, v38, v39, vcc
	v_cmp_class_f32_e32 vcc, v31, v234
	s_nop 1
	v_cndmask_b32_e32 v31, v38, v31, vcc
	v_div_scale_f32 v38, s[0:1], v31, v31, 1.0
	v_rcp_f32_e32 v39, v38
	s_nop 0
	v_fma_f32 v54, -v38, v39, 1.0
	v_fmac_f32_e32 v39, v54, v39
	v_div_scale_f32 v54, vcc, 1.0, v31, 1.0
	v_mul_f32_e32 v55, v54, v39
	v_fma_f32 v66, -v38, v55, v54
	v_fmac_f32_e32 v55, v66, v39
	v_fma_f32 v38, -v38, v55, v54
	v_div_fmas_f32 v38, v38, v39, v55
	v_div_fixup_f32 v38, v38, v31, 1.0
	v_pk_mul_f32 v[54:55], v[56:57], v[38:39] op_sel_hi:[1,0]
	s_nop 0
	v_pk_fma_f32 v[16:17], v[16:17], v[54:55], v[20:21]
	v_pk_mul_f32 v[20:21], v[68:69], v[38:39] op_sel_hi:[1,0]
	v_pk_fma_f32 v[16:17], v[30:31], v[58:59], v[16:17] op_sel_hi:[0,1,1]
	v_pk_mul_f32 v[12:13], v[12:13], v[16:17]
	v_pk_mul_f32 v[16:17], v[48:49], v[38:39] op_sel_hi:[1,0]
	v_cvt_pk_bf16_f32 v12, v12, v13
	v_pk_fma_f32 v[16:17], v[18:19], v[16:17], v[22:23]
	s_nop 0
	v_pk_fma_f32 v[16:17], v[30:31], v[50:51], v[16:17] op_sel_hi:[0,1,1]
	v_pk_mul_f32 v[14:15], v[14:15], v[16:17]
	s_nop 0
	v_cvt_pk_bf16_f32 v13, v14, v15
	global_store_dwordx2 v[40:41], v[12:13], off
	s_nop 0
	s_waitcnt vmcnt(1)
	v_pk_fma_f32 v[12:13], v[152:153], v[20:21], v[156:157]
	s_nop 0
	v_pk_fma_f32 v[12:13], v[30:31], v[70:71], v[12:13] op_sel_hi:[0,1,1]
	v_pk_mul_f32 v[8:9], v[8:9], v[12:13]
	v_pk_mul_f32 v[12:13], v[62:63], v[38:39] op_sel_hi:[1,0]
	v_cvt_pk_bf16_f32 v8, v8, v9
	v_pk_fma_f32 v[12:13], v[154:155], v[12:13], v[158:159]
	v_pk_mul_f32 v[18:19], v[82:83], v[38:39] op_sel_hi:[1,0]
	v_pk_fma_f32 v[12:13], v[30:31], v[64:65], v[12:13] op_sel_hi:[0,1,1]
	v_pk_mul_f32 v[10:11], v[10:11], v[12:13]
	v_lshlrev_b32_e32 v16, 16, v60
	v_cvt_pk_bf16_f32 v9, v10, v11
	global_store_dwordx2 v[52:53], v[8:9], off
	s_nop 0
	v_and_b32_e32 v17, 0xffff0000, v60
	s_waitcnt vmcnt(1)
	v_pk_fma_f32 v[8:9], v[160:161], v[18:19], v[164:165]
	s_nop 0
	v_pk_fma_f32 v[8:9], v[30:31], v[16:17], v[8:9] op_sel_hi:[0,1,1]
	v_pk_mul_f32 v[12:13], v[42:43], v[38:39] op_sel_hi:[1,0]
	v_pk_mul_f32 v[4:5], v[4:5], v[8:9]
	v_lshlrev_b32_e32 v8, 16, v61
	v_and_b32_e32 v9, 0xffff0000, v61
	v_pk_fma_f32 v[10:11], v[162:163], v[12:13], v[166:167] op_sel:[0,1,0] op_sel_hi:[1,0,1]
	v_cvt_pk_bf16_f32 v4, v4, v5
	v_pk_fma_f32 v[8:9], v[30:31], v[8:9], v[10:11] op_sel_hi:[0,1,1]
	v_pk_mul_f32 v[6:7], v[6:7], v[8:9]
	v_pk_mul_f32 v[16:17], v[34:35], v[38:39] op_sel_hi:[1,0]
	v_cvt_pk_bf16_f32 v5, v6, v7
	v_lshl_add_u64 v[6:7], v[26:27], 0, v[28:29]
	global_store_dwordx2 v[6:7], v[4:5], off
	s_nop 0
	global_load_dwordx2 v[12:13], v[36:37], off offset:96
	s_waitcnt vmcnt(1)
	v_pk_fma_f32 v[4:5], v[168:169], v[16:17], v[172:173] op_sel:[0,1,0] op_sel_hi:[1,0,1]
	s_waitcnt vmcnt(0)
	v_lshlrev_b32_e32 v14, 16, v12
	v_and_b32_e32 v15, 0xffff0000, v12
	v_pk_fma_f32 v[4:5], v[30:31], v[14:15], v[4:5] op_sel_hi:[0,1,1]
	v_pk_mul_f32 v[8:9], v[32:33], v[38:39] op_sel_hi:[1,0]
	v_pk_mul_f32 v[0:1], v[0:1], v[4:5]
	v_lshlrev_b32_e32 v4, 16, v13
	v_and_b32_e32 v5, 0xffff0000, v13
	v_pk_fma_f32 v[6:7], v[170:171], v[8:9], v[174:175] op_sel:[0,1,0] op_sel_hi:[1,0,1]
	v_cvt_pk_bf16_f32 v0, v0, v1
	v_pk_fma_f32 v[4:5], v[30:31], v[4:5], v[6:7] op_sel_hi:[0,1,1]
	v_pk_mul_f32 v[2:3], v[2:3], v[4:5]
	s_nop 0
	v_cvt_pk_bf16_f32 v1, v2, v3
	v_lshl_add_u64 v[2:3], v[26:27], 0, v[24:25]
	global_store_dwordx2 v[2:3], v[0:1], off
	s_cbranch_scc0 .LBB0_986
